# chunk rel-pos units: next-unit prefetch (K/V pair, Q, rfar, rel-bias column) added to FoX/MLA prefetch; prefetched units skip prologue vmcnt waits
# speedup vs baseline: 1.0127x; 1.0106x over previous
.LBB0_214:
	s_or_b64 exec, exec, s[4:5]
	s_cmpk_gt_i32 s38, 0x3ff
	s_mov_b64 s[4:5], -1
	s_cbranch_scc0 .LBB0_232
	s_add_i32 s4, s38, 0xfffffc00
	v_mov_b32_e32 v2, v216
	s_lshr_b32 s4, s4, 6
	s_sub_i32 s7, 15, s4
	v_readfirstlane_b32 s6, v2
	s_ashr_i32 s9, s6, 6
	s_lshl_b32 s4, s38, 9
	s_and_b32 s28, s38, 7
	s_and_b32 s34, s4, 0x7000
	s_lshl_b32 s4, s7, 8
	s_lshl_b32 s5, s9, 5
	v_and_b32_e32 v3, 31, v2
	s_add_i32 s5, s5, s4
	s_lshl_b32 s8, s28, 7
	v_readlane_b32 s4, v255, 4
	v_or_b32_e32 v0, s5, v3
	s_add_u32 s4, s4, s8
	v_readlane_b32 s5, v255, 5
	s_addc_u32 s5, s5, 0
	v_readlane_b32 s12, v255, 6
	s_add_u32 s12, s12, s8
	v_readlane_b32 s13, v255, 7
	v_and_b32_e32 v1, 63, v2
	s_addc_u32 s13, s13, 0
	v_readlane_b32 s14, v255, 8
	s_add_u32 s18, s14, s8
	v_readlane_b32 s8, v255, 9
	v_or_b32_e32 v1, s34, v1
	s_addc_u32 s19, s8, 0
	v_lshlrev_b32_e32 v192, 10, v1
	s_and_b32 s14, s9, 3
	v_bfe_u32 v1, v2, 2, 4
	v_lshl_add_u64 v[6:7], s[12:13], 0, v[192:193]
	s_lshl_b32 s12, s9, 3
	v_lshl_or_b32 v1, s14, 4, v1
	s_ashr_i32 s13, s12, 31
	v_or_b32_e32 v1, s34, v1
	s_ashr_i32 s15, s6, 8
	v_lshl_add_u64 v[162:163], s[12:13], 1, v[6:7]
	v_lshlrev_b32_e32 v192, 10, v1
	s_lshl_b32 s12, s15, 5
	v_lshl_add_u64 v[6:7], s[18:19], 0, v[192:193]
	s_ashr_i32 s13, s12, 31
	v_lshl_add_u64 v[8:9], s[12:13], 1, v[6:7]
	v_lshlrev_b32_e32 v6, 3, v2
	s_lshl_b32 s7, s7, 2
	v_and_b32_e32 v5, 24, v6
	v_sub_u32_e64 v10, s7, 8 clamp
	v_lshlrev_b32_e32 v192, 1, v5
	v_lshl_add_u64 v[166:167], v[8:9], 0, v[192:193]
	v_lshlrev_b32_e32 v192, 16, v10
	s_lshl_b32 s29, s9, 10
	v_lshl_add_u64 v[8:9], v[162:163], 0, v[192:193]
	s_add_i32 s29, s29, 0
	s_cmp_lg_u32 s32, 0
	s_cbranch_scc1 .Lpf3_s0
	s_mov_b32 s9, m0
	s_mov_b32 m0, s29
	s_nop 0
	global_load_lds_dwordx4 v[8:9], off
	s_mov_b32 m0, s9
.Lpf3_s0:
	s_lshl_b32 s9, s15, 12
	s_lshl_b32 s12, s14, 10
	s_or_b32 s9, s12, s9
	s_add_i32 s9, s9, 0
	s_max_u32 s8, s7, 8
	v_lshl_add_u64 v[8:9], v[166:167], 0, v[192:193]
	s_add_i32 s36, s9, 0xc000
	s_cmp_lg_u32 s32, 0
	s_cbranch_scc1 .Lpf3_s1
	s_mov_b32 s12, m0
	s_mov_b32 m0, s36
	s_nop 0
	global_load_lds_dwordx4 v[8:9], off
	s_mov_b32 m0, s12
.Lpf3_s1:
	s_add_i32 s12, s8, -7
	s_mov_b32 s13, s35
	s_lshl_b64 s[12:13], s[12:13], 16
	v_lshl_add_u64 v[8:9], v[162:163], 0, s[12:13]
	v_ashrrev_i32_e32 v1, 31, v0
	s_add_i32 s14, s29, 0x3000
	s_cmp_lg_u32 s32, 0
	s_cbranch_scc1 .Lpf3_s2
	s_mov_b32 s15, m0
	s_mov_b32 m0, s14
	s_nop 0
	global_load_lds_dwordx4 v[8:9], off
	s_mov_b32 m0, s15
.Lpf3_s2:
	v_lshl_add_u64 v[8:9], v[166:167], 0, s[12:13]
	v_lshl_add_u64 v[164:165], v[0:1], 0, s[34:35]
	v_bfe_u32 v4, v2, 5, 1
	s_add_i32 s9, s9, 0xe000
	s_cmp_lg_u32 s32, 0
	s_cbranch_scc1 .Lpf3_s3
	s_mov_b32 s12, m0
	s_mov_b32 m0, s9
	s_nop 0
	global_load_lds_dwordx4 v[8:9], off
	s_mov_b32 m0, s12
.Lpf3_s3:
	v_lshlrev_b64 v[8:9], 10, v[164:165]
	v_lshl_add_u64 v[8:9], s[4:5], 0, v[8:9]
	v_lshlrev_b32_e32 v192, 4, v4
	v_lshl_add_u64 v[8:9], v[8:9], 0, v[192:193]
	s_cmp_lg_u32 s32, 0
	s_cbranch_scc1 .Lpf3_q1
	global_load_dwordx4 v[112:115], v[8:9], off
	global_load_dwordx4 v[116:119], v[8:9], off offset:32
	global_load_dwordx4 v[120:123], v[8:9], off offset:64
	global_load_dwordx4 v[124:127], v[8:9], off offset:96
	s_branch .Lpf3_q2
.Lpf3_q1:
	v_mov_b32_e32 v112, v242
	v_mov_b32_e32 v113, v243
	v_mov_b32_e32 v114, v244
	v_mov_b32_e32 v115, v245
	v_mov_b32_e32 v116, v246
	v_mov_b32_e32 v117, v247
	v_mov_b32_e32 v118, v248
	v_mov_b32_e32 v119, v249
	v_mov_b32_e32 v120, v212
	v_mov_b32_e32 v121, v213
	v_mov_b32_e32 v122, v214
	v_mov_b32_e32 v123, v215
	v_mov_b32_e32 v124, v250
	v_mov_b32_e32 v125, v251
	v_mov_b32_e32 v126, v208
	v_mov_b32_e32 v127, v209
.Lpf3_q2:
	s_movk_i32 s4, 0x140
	s_mov_b32 s20, s90
	v_readfirstlane_b32 s34, v10
	v_cmp_gt_i32_e32 vcc, s4, v2
	s_and_b32 s4, s38, 63
	s_lshl_b32 s4, s4, 2
	s_or_b32 s4, s4, 0x27e0
	v_mov_b32_e32 v11, s4
	v_readlane_b32 s12, v253, 26
	v_readlane_b32 s13, v253, 27
	s_nop 4
	s_cmp_lg_u32 s32, 0
	s_cbranch_scc1 .Lpf3_r1
	global_load_dword v11, v11, s[12:13]
	s_and_saveexec_b64 s[4:5], vcc
	s_cbranch_execz .Lt3_skiprel
	v_or_b32_e32 v6, s28, v6
	v_ashrrev_i32_e32 v7, 31, v6
	v_lshl_add_u64 v[6:7], v[6:7], 2, s[12:13]
	global_load_dword v1, v[6:7], off
.Lt3_skiprel:
	s_or_b64 exec, exec, s[4:5]
	s_waitcnt vmcnt(0)
	s_branch .Lpf3_r2
.Lpf3_r1:
	v_mov_b32_e32 v11, v190
	s_and_saveexec_b64 s[4:5], vcc
	v_lshlrev_b32_e32 v6, 2, v2
	v_add_u32_e32 v6, 0x16000, v6
	ds_read_b32 v1, v6
	s_or_b64 exec, exec, s[4:5]
	s_waitcnt lgkmcnt(0)
.Lpf3_r2:
	s_and_saveexec_b64 s[4:5], vcc
	s_cbranch_execz .LBB0_217
	v_lshl_add_u32 v6, v2, 2, 0
	v_add_u32_e32 v6, 0x14000, v6
	v_mul_f32_e32 v1, 0x3fb8aa3b, v1
	ds_write_b32 v6, v1
.LBB0_217:
	s_or_b64 exec, exec, s[4:5]
	v_mov_b32_e32 v32, 0
	v_mov_b32_e32 v161, 0
	v_lshlrev_b32_e32 v160, 2, v4
	s_sub_i32 s4, s7, s8
	s_add_i32 s4, s4, 12
	s_ashr_i32 s37, s4, 1
	s_cmp_lt_i32 s37, 1
	v_mul_f32_e32 v168, 0x3fb8aa3b, v11
	s_cmp_lg_u32 s32, 0
	s_cbranch_scc1 .Lpf3_wb
	s_waitcnt vmcnt(0)
.Lpf3_wb:
	s_mov_b32 s32, 0
	s_waitcnt lgkmcnt(0)
	s_barrier
	s_cmp_lt_i32 s37, 1
	s_cbranch_scc1 .LBB0_233
	v_lshlrev_b32_e32 v1, 1, v2
	v_lshrrev_b32_e32 v2, 2, v2
	s_ashr_i32 s39, s6, 7
	v_and_or_b32 v2, v2, 3, v160
	s_add_i32 s39, s39, s7
	v_and_b32_e32 v1, 32, v1
	v_lshlrev_b32_e32 v3, 4, v3
	v_lshlrev_b32_e32 v4, 10, v4
	v_lshl_add_u32 v2, v2, 6, 0
	v_mov_b32_e32 v192, v193
	s_max_i32 s40, s39, 8
	v_add3_u32 v185, 0, v4, v3
	v_add3_u32 v186, v2, v1, v5
	v_sub_u32_e32 v187, v0, v160
	v_mov_b32_e32 v194, v193
	v_mov_b32_e32 v195, v193
	v_mov_b32_e32 v196, v193
	v_mov_b32_e32 v197, v193
	v_mov_b32_e32 v198, v193
	v_mov_b32_e32 v199, v193
	v_mov_b32_e32 v200, v193
	v_mov_b32_e32 v201, v193
	v_mov_b32_e32 v202, v193
	v_mov_b32_e32 v203, v193
	v_mov_b32_e32 v204, v193
	v_mov_b32_e32 v205, v193
	v_mov_b32_e32 v206, v193
	v_mov_b32_e32 v207, v193
	v_mov_b64_e32 v[16:17], v[192:193]
	v_mov_b64_e32 v[0:1], v[192:193]
	s_add_i32 s40, s40, -8
	v_mov_b32_e32 v33, v32
	v_mov_b32_e32 v34, v32
	v_mov_b32_e32 v35, v32
	v_mov_b32_e32 v36, v32
	v_mov_b32_e32 v37, v32
	v_mov_b32_e32 v38, v32
	v_mov_b32_e32 v39, v32
	v_mov_b32_e32 v40, v32
	v_mov_b32_e32 v41, v32
	v_mov_b32_e32 v42, v32
	v_mov_b32_e32 v43, v32
	v_mov_b32_e32 v44, v32
	v_mov_b32_e32 v45, v32
	v_mov_b32_e32 v46, v32
	v_mov_b32_e32 v47, v32
	s_add_i32 s18, s39, -4
	s_mov_b32 s19, 0
	v_mov_b32_e32 v169, v168
	v_mov_b32_e32 v170, v168
	v_mov_b32_e32 v171, v168
	v_mov_b32_e32 v172, v168
	v_mov_b32_e32 v173, v168
	v_mov_b32_e32 v174, v168
	v_mov_b32_e32 v175, v168
	v_mov_b32_e32 v176, v168
	v_mov_b32_e32 v177, v168
	v_mov_b32_e32 v178, v168
	v_mov_b32_e32 v179, v168
	v_mov_b32_e32 v180, v168
	v_mov_b32_e32 v181, v168
	v_mov_b32_e32 v182, v168
	v_mov_b32_e32 v183, v168
	v_mov_b32_e32 v161, 0
	v_mov_b64_e32 v[18:19], v[194:195]
	v_mov_b64_e32 v[20:21], v[196:197]
	v_mov_b64_e32 v[22:23], v[198:199]
	v_mov_b64_e32 v[24:25], v[200:201]
	v_mov_b64_e32 v[26:27], v[202:203]
	v_mov_b64_e32 v[28:29], v[204:205]
	v_mov_b64_e32 v[30:31], v[206:207]
	v_mov_b64_e32 v[2:3], v[194:195]
	v_mov_b64_e32 v[4:5], v[196:197]
	v_mov_b64_e32 v[6:7], v[198:199]
	v_mov_b64_e32 v[8:9], v[200:201]
	v_mov_b64_e32 v[10:11], v[202:203]
	v_mov_b64_e32 v[12:13], v[204:205]
	v_mov_b64_e32 v[14:15], v[206:207]
	s_mov_b32 s90, s20
	s_branch .LBB0_220
.Lpf3_block:
	s_xor_b32 s5, s21, 1
	s_lshl_b32 s5, s5, 2
	s_add_i32 s5, s5, 0x15500
	v_mov_b32_e32 v48, s5
	ds_read_b32 v48, v48
	s_waitcnt lgkmcnt(0)
	v_readfirstlane_b32 s5, v48
	s_sub_i32 s5, s5, 0x400
	s_cmp_lt_u32 s5, 0x400
	s_cbranch_scc0 .LBB0_222
	s_mov_b32 s32, 1
	s_and_b32 s6, s5, 7
	s_lshl_b32 s6, s6, 7
	s_lshr_b32 s7, s5, 3
	s_and_b32 s7, s7, 7
	s_lshl_b32 s7, s7, 12
	s_lshr_b32 s5, s5, 6
	s_sub_i32 s5, 15, s5
	s_lshl_b32 s8, s5, 2
	s_sub_i32 s8, s8, 8
	s_max_i32 s8, s8, 0
	s_lshl_b32 s9, s7, 10
	s_add_u32 s9, s9, s6
	s_lshl_b32 s8, s8, 16
	s_add_u32 s9, s9, s8
	v_readlane_b32 vcc_lo, v255, 6
	v_readlane_b32 vcc_hi, v255, 7
	s_add_u32 vcc_lo, vcc_lo, s9
	s_addc_u32 vcc_hi, vcc_hi, 0
	v_and_b32_e32 v48, 63, v216
	v_lshrrev_b32_e32 v49, 6, v216
	v_lshlrev_b32_e32 v48, 10, v48
	v_lshl_or_b32 v48, v49, 4, v48
	s_mov_b32 m0, s29
	s_nop 0
	global_load_lds_dwordx4 v48, vcc
	s_add_u32 vcc_lo, vcc_lo, 0x10000
	s_addc_u32 vcc_hi, vcc_hi, 0
	s_add_i32 m0, s29, 0x3000
	s_nop 0
	global_load_lds_dwordx4 v48, vcc
	v_readlane_b32 vcc_lo, v255, 8
	v_readlane_b32 vcc_hi, v255, 9
	s_add_u32 vcc_lo, vcc_lo, s9
	s_addc_u32 vcc_hi, vcc_hi, 0
	v_and_b32_e32 v50, 63, v216
	v_lshrrev_b32_e32 v51, 2, v50
	v_and_b32_e32 v52, 3, v49
	v_lshl_or_b32 v51, v52, 4, v51
	v_lshlrev_b32_e32 v51, 10, v51
	v_lshrrev_b32_e32 v52, 2, v49
	v_lshl_or_b32 v51, v52, 6, v51
	v_and_b32_e32 v50, 3, v50
	v_lshl_or_b32 v50, v50, 4, v51
	s_mov_b32 m0, s36
	s_nop 0
	global_load_lds_dwordx4 v50, vcc
	s_add_u32 vcc_lo, vcc_lo, 0x10000
	s_addc_u32 vcc_hi, vcc_hi, 0
	s_add_i32 m0, s36, 0x2000
	s_nop 0
	global_load_lds_dwordx4 v50, vcc
	v_readlane_b32 vcc_lo, v255, 4
	v_readlane_b32 vcc_hi, v255, 5
	s_lshl_b32 s8, s5, 8
	s_add_i32 s8, s8, s7
	s_lshl_b32 s8, s8, 10
	s_add_u32 s8, s8, s6
	s_add_u32 vcc_lo, vcc_lo, s8
	s_addc_u32 vcc_hi, vcc_hi, 0
	v_and_b32_e32 v50, 31, v216
	v_lshl_or_b32 v50, v49, 5, v50
	v_lshlrev_b32_e32 v51, 10, v50
	v_bfe_u32 v52, v216, 5, 1
	v_lshl_or_b32 v51, v52, 4, v51
	global_load_dwordx4 v[242:245], v51, vcc
	global_load_dwordx4 v[246:249], v51, vcc offset:32
	global_load_dwordx4 v[212:215], v51, vcc offset:64
	global_load_dwordx2 v[250:251], v51, vcc offset:96
	global_load_dwordx2 v[208:209], v51, vcc offset:104
	v_readlane_b32 vcc_lo, v253, 26
	v_readlane_b32 vcc_hi, v253, 27
	s_lshr_b32 s6, s6, 5
	s_add_i32 s8, s6, 0x27e0
	v_mov_b32_e32 v50, s8
	s_nop 4
	global_load_dword v190, v50, vcc
	v_readfirstlane_b32 s8, v49
	s_cmp_gt_u32 s8, 4
	s_cbranch_scc1 .LBB0_222
	v_lshlrev_b32_e32 v50, 5, v216
	v_add_u32_e32 v50, s6, v50
	s_lshl_b32 s8, s8, 8
	s_add_i32 m0, s8, 0x16000
	s_nop 0
	global_load_lds_dword v50, vcc
	s_branch .LBB0_222
.LBB0_219:
	s_cmp_lg_u32 s19, 1
	s_cbranch_scc1 .Lpf3_nosu
	v_readfirstlane_b32 vcc_lo, v216
	s_cmp_lt_u32 vcc_lo, 64
	s_cbranch_scc0 .Lpf3_nosu
	s_waitcnt vmcnt(0)
	v_readfirstlane_b32 vcc_lo, v184
	s_xor_b32 vcc_hi, s21, 1
	s_lshl_b32 vcc_hi, vcc_hi, 2
	s_add_i32 vcc_hi, vcc_hi, 0x15500
	v_mov_b32_e32 v48, vcc_hi
	v_mov_b32_e32 v49, vcc_lo
	ds_write_b32 v48, v49

.Lpf2_c2:
	v_lshlrev_b32_e32 v160, 2, v9
	v_readlane_b32 s4, v253, 20
	v_lshlrev_b32_e32 v3, 1, v3
	v_and_or_b32 v5, v7, 3, v160
	v_add_u32_e32 v141, s4, v192
	s_lshl_b32 s4, s8, 2
	s_ashr_i32 s18, s18, 7
	v_and_b32_e32 v3, 32, v3
	s_add_i32 s18, s18, s4
	v_mov_b32_e32 v6, v193
	s_add_i32 s4, s4, 4
	v_mov_b32_e32 v192, v193
	v_mov_b32_e32 v194, v193
	v_mov_b32_e32 v195, v193
	v_mov_b32_e32 v196, v193
	v_mov_b32_e32 v197, v193
	v_mov_b32_e32 v198, v193
	v_mov_b32_e32 v199, v193
	v_mov_b32_e32 v200, v193
	v_mov_b32_e32 v201, v193
	v_mov_b32_e32 v202, v193
	v_mov_b32_e32 v203, v193
	v_mov_b32_e32 v204, v193
	v_mov_b32_e32 v205, v193
	v_mov_b32_e32 v206, v193
	v_mov_b32_e32 v207, v193
	s_lshr_b32 s19, s4, 1
	s_mov_b32 s37, 0
	v_mov_b32_e32 v143, 0
	s_cmp_lg_u32 s32, 0
	s_cbranch_scc1 .Lpf2_w4
	s_waitcnt vmcnt(3)
.Lpf2_w4:
	s_cmp_lg_u32 s32, 0
	s_cbranch_scc1 .Lpf2_w3
	s_waitcnt vmcnt(2)
.Lpf2_w3:
	s_cmp_lg_u32 s32, 0
	s_cbranch_scc1 .Lpf2_w2
	s_waitcnt vmcnt(1)
.Lpf2_w2:
	s_cmp_lg_u32 s32, 0
	s_cbranch_scc1 .Lpf2_w1
	s_waitcnt vmcnt(0)
.Lpf2_w1:
	v_lshlrev_b32_e32 v0, 10, v9
	v_lshlrev_b32_e32 v1, 4, v8
	v_add3_u32 v140, 0, v0, v1
	v_lshl_add_u32 v0, v5, 6, 0
	v_add3_u32 v142, v0, v3, v2
	v_lshl_or_b32 v0, s18, 6, v160
	v_cmp_gt_i32_e64 s[42:43], v0, v4
	v_cmp_lt_i32_e64 s[44:45], v0, v4
	v_or_b32_e32 v1, 3, v0
	v_or_b32_e32 v2, 2, v0
	v_or_b32_e32 v3, 9, v0
	v_or_b32_e32 v5, 8, v0
	v_or_b32_e32 v7, 11, v0
	v_or_b32_e32 v8, 10, v0
	v_or_b32_e32 v9, 17, v0
	v_or_b32_e32 v10, 16, v0
	v_or_b32_e32 v11, 19, v0
	v_or_b32_e32 v12, 18, v0
	v_or_b32_e32 v13, 25, v0
	v_or_b32_e32 v14, 24, v0
	v_or_b32_e32 v15, 27, v0
	v_or_b32_e32 v16, 26, v0
	v_or_b32_e32 v17, 32, v0
	v_or_b32_e32 v18, 33, v0
	v_or_b32_e32 v19, 34, v0
	v_or_b32_e32 v20, 35, v0
	v_or_b32_e32 v21, 40, v0
	v_or_b32_e32 v22, 41, v0
	v_or_b32_e32 v23, 42, v0
	v_or_b32_e32 v24, 43, v0
	v_or_b32_e32 v25, 48, v0
	v_or_b32_e32 v26, 49, v0
	v_or_b32_e32 v27, 50, v0
	v_or_b32_e32 v28, 51, v0
	v_or_b32_e32 v29, 56, v0
	v_or_b32_e32 v30, 57, v0
	v_or_b32_e32 v31, 58, v0
	v_or_b32_e32 v0, 59, v0
	s_cmp_lg_u32 s32, 0
	s_cbranch_scc1 .Lpf2_w0
	s_waitcnt vmcnt(0)

.Lpf2_wb:
	s_mov_b32 s32, 0
	s_waitcnt lgkmcnt(0)
	s_barrier
	v_cmp_gt_i32_e64 s[46:47], v1, v4
	v_cmp_gt_i32_e64 s[48:49], v2, v4
	v_cmp_gt_i32_e64 s[50:51], v3, v4
	v_cmp_gt_i32_e64 s[52:53], v5, v4
	v_cmp_gt_i32_e64 s[54:55], v7, v4
	v_cmp_gt_i32_e64 s[56:57], v8, v4
	v_cmp_gt_i32_e64 s[58:59], v9, v4
	v_cmp_gt_i32_e64 s[60:61], v10, v4
	v_cmp_gt_i32_e64 s[62:63], v11, v4
	v_cmp_gt_i32_e64 s[64:65], v12, v4
	v_cmp_gt_i32_e64 s[66:67], v13, v4
	v_cmp_gt_i32_e64 s[68:69], v14, v4
	v_cmp_gt_i32_e64 s[70:71], v15, v4
	v_cmp_gt_i32_e64 s[72:73], v16, v4
	v_cmp_gt_i32_e64 s[74:75], v0, v4
	v_cmp_gt_i32_e64 s[76:77], v31, v4
	v_cmp_gt_i32_e64 s[78:79], v30, v4
	v_cmp_gt_i32_e64 s[80:81], v29, v4
	v_cmp_gt_i32_e64 s[82:83], v28, v4
	v_cmp_gt_i32_e64 s[84:85], v27, v4
	v_cmp_gt_i32_e64 s[86:87], v26, v4
	v_cmp_gt_i32_e64 s[88:89], v25, v4
	v_cmp_gt_i32_e64 s[90:91], v24, v4
	v_cmp_gt_i32_e64 s[92:93], v23, v4
	v_cmp_gt_i32_e64 s[94:95], v22, v4
	v_cmp_gt_i32_e64 s[96:97], v21, v4
	v_cmp_gt_i32_e64 s[98:99], v20, v4
	v_cmp_gt_i32_e64 s[38:39], v19, v4
	v_cmp_gt_i32_e64 s[4:5], v18, v4
	v_cmp_gt_i32_e64 s[6:7], v17, v4
	v_mov_b64_e32 v[16:17], v[192:193]
	v_mov_b64_e32 v[0:1], v[192:193]
	v_mov_b32_e32 v33, v32
	v_mov_b32_e32 v34, v32
	v_mov_b32_e32 v35, v32
	v_mov_b32_e32 v36, v32
	v_mov_b32_e32 v37, v32
	v_mov_b32_e32 v38, v32
	v_mov_b32_e32 v39, v32
	v_mov_b32_e32 v40, v32
	v_mov_b32_e32 v41, v32
	v_mov_b32_e32 v42, v32
	v_mov_b32_e32 v43, v32
	v_mov_b32_e32 v44, v32
	v_mov_b32_e32 v45, v32
	v_mov_b32_e32 v46, v32
	v_mov_b32_e32 v47, v32
	v_mov_b64_e32 v[18:19], v[194:195]
	v_mov_b64_e32 v[20:21], v[196:197]
	v_mov_b64_e32 v[22:23], v[198:199]
	v_mov_b64_e32 v[24:25], v[200:201]
	v_mov_b64_e32 v[26:27], v[202:203]
	v_mov_b64_e32 v[28:29], v[204:205]
	v_mov_b64_e32 v[30:31], v[206:207]
	v_mov_b64_e32 v[2:3], v[194:195]
	v_mov_b64_e32 v[4:5], v[196:197]
	v_mov_b64_e32 v[6:7], v[198:199]
	v_mov_b64_e32 v[8:9], v[200:201]
	v_mov_b64_e32 v[10:11], v[202:203]
	v_mov_b64_e32 v[12:13], v[204:205]
	v_mov_b64_e32 v[14:15], v[206:207]
	s_branch .LBB0_243

.LBB0_242:
	s_cmp_lg_u32 s37, 1
	s_cbranch_scc1 .Lpf2_nosu
	v_readfirstlane_b32 vcc_lo, v216
	s_cmp_lt_u32 vcc_lo, 64
	s_cbranch_scc0 .Lpf2_nosu
	s_waitcnt vmcnt(0)
	v_readfirstlane_b32 vcc_lo, v184
	v_readlane_b32 vcc_hi, v255, 63
	s_xor_b32 vcc_hi, vcc_hi, 1
	s_lshl_b32 vcc_hi, vcc_hi, 2
	s_add_i32 vcc_hi, vcc_hi, 0x15500
	v_mov_b32_e32 v48, vcc_hi
	v_mov_b32_e32 v49, vcc_lo
	ds_write_b32 v48, v49

.Lpf0_q2:
	v_mov_b32_e32 v0, v193
	v_lshlrev_b32_e32 v1, 4, v4
	v_lshlrev_b32_e32 v136, 2, v5
	v_lshrrev_b32_e32 v4, 2, v2
	v_and_or_b32 v4, v4, 3, v136
	v_lshlrev_b32_e32 v2, 1, v2
	s_lshl_b32 s8, s8, 2
	v_and_b32_e32 v2, 32, v2
	v_mov_b32_e32 v192, v193
	s_add_i32 s28, s28, s8
	s_add_i32 s8, s8, 4
	v_mov_b32_e32 v194, v193
	v_mov_b32_e32 v195, v193
	v_mov_b32_e32 v196, v193
	v_mov_b32_e32 v197, v193
	v_mov_b32_e32 v198, v193
	v_mov_b32_e32 v199, v193
	v_mov_b32_e32 v200, v193
	v_mov_b32_e32 v201, v193
	v_mov_b32_e32 v202, v193
	v_mov_b32_e32 v203, v193
	v_mov_b32_e32 v204, v193
	v_mov_b32_e32 v205, v193
	v_mov_b32_e32 v206, v193
	v_mov_b32_e32 v207, v193
	s_mov_b32 s18, 0
	s_lshr_b32 s19, s8, 1
	s_add_i32 s20, s39, 0x2000
	v_mov_b32_e32 v148, 0
	s_cmp_lg_u32 s32, 0
	s_cbranch_scc1 .Lpf0_w3
	s_waitcnt vmcnt(3)
.Lpf0_w3:
	v_lshlrev_b32_e32 v32, 16, v12
	v_and_b32_e32 v33, 0xffff0000, v12
	v_lshlrev_b32_e32 v6, 16, v8
	v_and_b32_e32 v7, 0xffff0000, v8
	v_pk_mul_f32 v[34:35], v[28:29], v[32:33]
	v_lshlrev_b32_e32 v8, 16, v13
	v_pk_fma_f32 v[34:35], v[20:21], v[6:7], v[34:35] neg_lo:[0,0,1] neg_hi:[0,0,1]
	v_pk_mul_f32 v[6:7], v[28:29], v[6:7]
	v_cvt_pk_bf16_f32 v80, v34, v35
	v_pk_fma_f32 v[6:7], v[20:21], v[32:33], v[6:7]
	v_mov_b32_e32 v32, v193
	v_cvt_pk_bf16_f32 v84, v6, v7
	v_lshlrev_b32_e32 v6, 16, v9
	v_and_b32_e32 v7, 0xffff0000, v9
	v_and_b32_e32 v9, 0xffff0000, v13
	v_pk_mul_f32 v[12:13], v[30:31], v[8:9]
	s_cmp_lg_u32 s32, 0
	s_cbranch_scc1 .Lpf0_w2
	s_waitcnt vmcnt(2)

.Lpf0_w0:
	v_pk_fma_f32 v[12:13], v[22:23], v[6:7], v[12:13] neg_lo:[0,0,1] neg_hi:[0,0,1]
	v_pk_mul_f32 v[6:7], v[30:31], v[6:7]
	v_cvt_pk_bf16_f32 v81, v12, v13
	v_pk_fma_f32 v[6:7], v[22:23], v[8:9], v[6:7]
	v_lshlrev_b32_e32 v8, 16, v14
	v_and_b32_e32 v9, 0xffff0000, v14
	v_cvt_pk_bf16_f32 v85, v6, v7
	v_lshlrev_b32_e32 v6, 16, v10
	v_and_b32_e32 v7, 0xffff0000, v10
	v_pk_mul_f32 v[12:13], v[24:25], v[8:9]
	s_nop 0
	v_pk_fma_f32 v[12:13], v[16:17], v[6:7], v[12:13] neg_lo:[0,0,1] neg_hi:[0,0,1]
	v_pk_mul_f32 v[6:7], v[24:25], v[6:7]
	v_cvt_pk_bf16_f32 v82, v12, v13
	v_pk_fma_f32 v[6:7], v[16:17], v[8:9], v[6:7]
	v_lshlrev_b32_e32 v8, 16, v15
	v_and_b32_e32 v9, 0xffff0000, v15
	v_cvt_pk_bf16_f32 v86, v6, v7
	v_lshlrev_b32_e32 v6, 16, v11
	v_and_b32_e32 v7, 0xffff0000, v11
	v_pk_mul_f32 v[10:11], v[26:27], v[8:9]
	s_nop 0
	v_pk_fma_f32 v[10:11], v[18:19], v[6:7], v[10:11] neg_lo:[0,0,1] neg_hi:[0,0,1]
	v_pk_mul_f32 v[6:7], v[26:27], v[6:7]
	v_cvt_pk_bf16_f32 v83, v10, v11
	v_pk_fma_f32 v[6:7], v[18:19], v[8:9], v[6:7]
	v_mov_b64_e32 v[16:17], v[192:193]
	v_cvt_pk_bf16_f32 v87, v6, v7
	s_cmp_lg_u32 s32, 0
	s_cbranch_scc1 .Lpf0_wb
	s_waitcnt vmcnt(0)
.Lpf0_wb:
	s_mov_b32 s32, 0
	s_waitcnt lgkmcnt(0)
	s_barrier
	v_mov_b64_e32 v[18:19], v[194:195]
	v_lshlrev_b32_e32 v0, 10, v5
	v_add3_u32 v137, 0, v0, v1
	v_lshl_add_u32 v0, v4, 6, 0
	v_add3_u32 v147, v0, v2, v3
	v_mov_b64_e32 v[0:1], v[192:193]
	v_mov_b32_e32 v33, v32
	v_mov_b32_e32 v34, v32
	v_mov_b32_e32 v35, v32
	v_mov_b32_e32 v36, v32
	v_mov_b32_e32 v37, v32
	v_mov_b32_e32 v38, v32
	v_mov_b32_e32 v39, v32
	v_mov_b32_e32 v40, v32
	v_mov_b32_e32 v41, v32
	v_mov_b32_e32 v42, v32
	v_mov_b32_e32 v43, v32
	v_mov_b32_e32 v44, v32
	v_mov_b32_e32 v45, v32
	v_mov_b32_e32 v46, v32
	v_mov_b32_e32 v47, v32
	v_mov_b64_e32 v[20:21], v[196:197]
	v_mov_b64_e32 v[22:23], v[198:199]
	v_mov_b64_e32 v[24:25], v[200:201]
	v_mov_b64_e32 v[26:27], v[202:203]
	v_mov_b64_e32 v[28:29], v[204:205]
	v_mov_b64_e32 v[30:31], v[206:207]
	v_mov_b64_e32 v[2:3], v[194:195]
	v_mov_b64_e32 v[4:5], v[196:197]
	v_mov_b64_e32 v[6:7], v[198:199]
	v_mov_b64_e32 v[8:9], v[200:201]
	v_mov_b64_e32 v[10:11], v[202:203]
	v_mov_b64_e32 v[12:13], v[204:205]
	v_mov_b64_e32 v[14:15], v[206:207]
	s_branch .LBB0_297

.LBB0_296:
	s_cmp_lg_u32 s18, 1
	s_cbranch_scc1 .Lpf0_nosu
	v_readfirstlane_b32 vcc_lo, v216
	s_cmp_lt_u32 vcc_lo, 64
	s_cbranch_scc0 .Lpf0_nosu
	s_waitcnt vmcnt(0)
	v_readfirstlane_b32 vcc_lo, v146
	s_mov_b32 vcc_hi, s44
	s_xor_b32 vcc_hi, vcc_hi, 1
	s_lshl_b32 vcc_hi, vcc_hi, 2
	s_add_i32 vcc_hi, vcc_hi, 0x15500
	v_mov_b32_e32 v48, vcc_hi
	v_mov_b32_e32 v49, vcc_lo
	ds_write_b32 v48, v49
